# GEMM K-loops: merged counted vmcnt/lgkmcnt waits into one s_waitcnt before each barrier and dropped the redundant post-barrier lgkmcnt(0)
# speedup vs baseline: 1.0060x; 1.0003x over previous
.LBB0_304:
	s_add_u32 s14, s12, 0x4000
	s_addc_u32 s15, s13, 0
	s_cmp_eq_u32 s50, 28
	s_cselect_b32 s22, s46, s14
	s_cselect_b32 s23, s47, s15
	s_cselect_b32 s16, s48, s41
	s_cselect_b32 s17, s49, s43
	s_add_u32 s14, s22, 0x8000
	s_addc_u32 s15, s23, 0
	s_add_i32 s51, 0, 0x10000
	s_add_i32 s54, 0, 0x14000
	ds_read_b128 v[38:41], v229
	ds_read_b128 v[42:45], v229 offset:1024
	ds_read_b128 v[50:53], v229 offset:2048
	ds_read_b128 v[54:57], v229 offset:3072
	ds_read_b128 v[146:149], v229 offset:16384
	ds_read_b128 v[150:153], v229 offset:17408
	ds_read_b128 v[166:169], v229 offset:18432
	ds_read_b128 v[170:173], v229 offset:19456
	s_add_i32 m0, s59, 0xc000
	ds_read_b128 v[174:177], v206
	ds_read_b128 v[178:181], v206 offset:1024
	ds_read_b128 v[182:185], v206 offset:2048
	ds_read_b128 v[186:189], v206 offset:3072
	ds_read_b128 v[190:193], v206 offset:4096
	ds_read_b128 v[194:197], v206 offset:5120
	ds_read_b128 v[198:201], v206 offset:6144
	ds_read_b128 v[212:215], v206 offset:7168
	global_load_lds_dwordx4 v154, s[12:13]
	s_add_i32 m0, s59, 0xe000
	s_nop 0
	global_load_lds_dwordx4 v156, s[12:13]
	s_waitcnt vmcnt(8) lgkmcnt(0)
	s_barrier
	s_setprio 1
	v_mfma_f32_16x16x32_bf16 v[142:145], v[38:41], v[174:177], v[142:145]
	v_mfma_f32_16x16x32_bf16 v[138:141], v[50:53], v[174:177], v[138:141]
	v_mfma_f32_16x16x32_bf16 v[126:129], v[38:41], v[182:185], v[126:129]
	v_mfma_f32_16x16x32_bf16 v[122:125], v[50:53], v[182:185], v[122:125]
	v_mfma_f32_16x16x32_bf16 v[110:113], v[38:41], v[190:193], v[110:113]
	v_mfma_f32_16x16x32_bf16 v[106:109], v[50:53], v[190:193], v[106:109]
	v_mfma_f32_16x16x32_bf16 v[94:97], v[38:41], v[198:201], v[94:97]
	v_mfma_f32_16x16x32_bf16 v[90:93], v[50:53], v[198:201], v[90:93]
	v_mfma_f32_16x16x32_bf16 v[142:145], v[42:45], v[178:181], v[142:145]
	v_mfma_f32_16x16x32_bf16 v[138:141], v[54:57], v[178:181], v[138:141]
	v_mfma_f32_16x16x32_bf16 v[126:129], v[42:45], v[186:189], v[126:129]
	v_mfma_f32_16x16x32_bf16 v[122:125], v[54:57], v[186:189], v[122:125]
	v_mfma_f32_16x16x32_bf16 v[110:113], v[42:45], v[194:197], v[110:113]
	v_mfma_f32_16x16x32_bf16 v[106:109], v[54:57], v[194:197], v[106:109]
	v_mfma_f32_16x16x32_bf16 v[94:97], v[42:45], v[212:215], v[94:97]
	v_mfma_f32_16x16x32_bf16 v[90:93], v[54:57], v[212:215], v[90:93]
	s_setprio 0
	s_setprio 1
	v_mfma_f32_16x16x32_bf16 v[134:137], v[146:149], v[174:177], v[134:137]
	v_mfma_f32_16x16x32_bf16 v[130:133], v[166:169], v[174:177], v[130:133]
	v_mfma_f32_16x16x32_bf16 v[118:121], v[146:149], v[182:185], v[118:121]
	v_mfma_f32_16x16x32_bf16 v[114:117], v[166:169], v[182:185], v[114:117]
	v_mfma_f32_16x16x32_bf16 v[102:105], v[146:149], v[190:193], v[102:105]
	v_mfma_f32_16x16x32_bf16 v[98:101], v[166:169], v[190:193], v[98:101]
	v_mfma_f32_16x16x32_bf16 v[86:89], v[146:149], v[198:201], v[86:89]
	v_mfma_f32_16x16x32_bf16 v[82:85], v[166:169], v[198:201], v[82:85]
	v_mfma_f32_16x16x32_bf16 v[134:137], v[150:153], v[178:181], v[134:137]
	v_mfma_f32_16x16x32_bf16 v[130:133], v[170:173], v[178:181], v[130:133]
	v_mfma_f32_16x16x32_bf16 v[118:121], v[150:153], v[186:189], v[118:121]
	v_mfma_f32_16x16x32_bf16 v[114:117], v[170:173], v[186:189], v[114:117]
	v_mfma_f32_16x16x32_bf16 v[102:105], v[150:153], v[194:197], v[102:105]
	v_mfma_f32_16x16x32_bf16 v[98:101], v[170:173], v[194:197], v[98:101]
	v_mfma_f32_16x16x32_bf16 v[86:89], v[150:153], v[212:215], v[86:89]
	v_mfma_f32_16x16x32_bf16 v[82:85], v[170:173], v[212:215], v[82:85]
	s_setprio 0
	s_barrier
	s_add_i32 s51, s51, s58
	s_mov_b32 m0, s51
	ds_read_b128 v[174:177], v206 offset:16384
	ds_read_b128 v[178:181], v206 offset:17408
	ds_read_b128 v[182:185], v206 offset:18432
	ds_read_b128 v[186:189], v206 offset:19456
	ds_read_b128 v[190:193], v206 offset:20480
	ds_read_b128 v[194:197], v206 offset:21504
	ds_read_b128 v[198:201], v206 offset:22528
	ds_read_b128 v[212:215], v206 offset:23552
	global_load_lds_dwordx4 v154, s[16:17]
	s_add_i32 m0, s51, 0x2000
	s_add_u32 s52, s16, 0x4000
	s_addc_u32 s53, s17, 0
	s_add_i32 s51, s54, s58
	global_load_lds_dwordx4 v156, s[16:17]
	s_mov_b32 m0, s51
	s_nop 0
	global_load_lds_dwordx4 v154, s[52:53]
	s_add_i32 m0, s51, 0x2000
	s_nop 0
	global_load_lds_dwordx4 v156, s[52:53]
	s_mov_b32 m0, s59
	s_nop 0
	global_load_lds_dwordx4 v154, s[22:23]
	s_mov_b32 m0, s60
	s_nop 0
	global_load_lds_dwordx4 v156, s[22:23]
	s_waitcnt vmcnt(8) lgkmcnt(0)
	s_barrier
	s_setprio 1
	v_mfma_f32_16x16x32_bf16 v[78:81], v[38:41], v[174:177], v[78:81]
	v_mfma_f32_16x16x32_bf16 v[74:77], v[50:53], v[174:177], v[74:77]
	v_mfma_f32_16x16x32_bf16 v[62:65], v[38:41], v[182:185], v[62:65]
	v_mfma_f32_16x16x32_bf16 v[58:61], v[50:53], v[182:185], v[58:61]
	v_mfma_f32_16x16x32_bf16 v[30:33], v[38:41], v[190:193], v[30:33]
	v_mfma_f32_16x16x32_bf16 v[26:29], v[50:53], v[190:193], v[26:29]
	v_mfma_f32_16x16x32_bf16 v[14:17], v[38:41], v[198:201], v[14:17]
	v_mfma_f32_16x16x32_bf16 v[10:13], v[50:53], v[198:201], v[10:13]
	v_mfma_f32_16x16x32_bf16 v[78:81], v[42:45], v[178:181], v[78:81]
	v_mfma_f32_16x16x32_bf16 v[74:77], v[54:57], v[178:181], v[74:77]
	v_mfma_f32_16x16x32_bf16 v[62:65], v[42:45], v[186:189], v[62:65]
	v_mfma_f32_16x16x32_bf16 v[58:61], v[54:57], v[186:189], v[58:61]
	v_mfma_f32_16x16x32_bf16 v[30:33], v[42:45], v[194:197], v[30:33]
	v_mfma_f32_16x16x32_bf16 v[26:29], v[54:57], v[194:197], v[26:29]
	v_mfma_f32_16x16x32_bf16 v[14:17], v[42:45], v[212:215], v[14:17]
	v_mfma_f32_16x16x32_bf16 v[10:13], v[54:57], v[212:215], v[10:13]
	s_setprio 0
	s_setprio 1
	v_mfma_f32_16x16x32_bf16 v[46:49], v[146:149], v[182:185], v[46:49]
	v_mfma_f32_16x16x32_bf16 v[34:37], v[166:169], v[182:185], v[34:37]
	v_mfma_f32_16x16x32_bf16 v[22:25], v[146:149], v[190:193], v[22:25]
	v_mfma_f32_16x16x32_bf16 v[18:21], v[166:169], v[190:193], v[18:21]
	v_mfma_f32_16x16x32_bf16 v[6:9], v[146:149], v[198:201], v[6:9]
	v_mfma_f32_16x16x32_bf16 v[2:5], v[166:169], v[198:201], v[2:5]
	v_mfma_f32_16x16x32_bf16 v[38:41], v[146:149], v[174:177], v[70:73]
	v_mfma_f32_16x16x32_bf16 v[42:45], v[166:169], v[174:177], v[66:69]
	v_mfma_f32_16x16x32_bf16 v[46:49], v[150:153], v[186:189], v[46:49]
	v_mfma_f32_16x16x32_bf16 v[34:37], v[170:173], v[186:189], v[34:37]
	v_mfma_f32_16x16x32_bf16 v[22:25], v[150:153], v[194:197], v[22:25]
	v_mfma_f32_16x16x32_bf16 v[18:21], v[170:173], v[194:197], v[18:21]
	v_mfma_f32_16x16x32_bf16 v[6:9], v[150:153], v[212:215], v[6:9]
	v_mfma_f32_16x16x32_bf16 v[2:5], v[170:173], v[212:215], v[2:5]
	v_mfma_f32_16x16x32_bf16 v[38:41], v[150:153], v[178:181], v[38:41]
	v_mfma_f32_16x16x32_bf16 v[42:45], v[170:173], v[178:181], v[42:45]
	s_setprio 0
	s_barrier
	s_add_i32 s51, 0, 0x18000
	s_add_i32 s52, 0, 0x1c000
	ds_read_b128 v[50:53], v229 offset:32768
	ds_read_b128 v[54:57], v229 offset:33792
	ds_read_b128 v[66:69], v229 offset:34816
	ds_read_b128 v[70:73], v229 offset:35840
	ds_read_b128 v[146:149], v229 offset:49152
	ds_read_b128 v[150:153], v229 offset:50176
	ds_read_b128 v[166:169], v229 offset:51200
	ds_read_b128 v[170:173], v229 offset:52224
	s_add_u32 s22, s22, 0x4000
	s_addc_u32 s23, s23, 0
	s_mov_b32 m0, s61
	ds_read_b128 v[174:177], v206 offset:32768
	ds_read_b128 v[178:181], v206 offset:33792
	ds_read_b128 v[182:185], v206 offset:34816
	ds_read_b128 v[186:189], v206 offset:35840
	ds_read_b128 v[190:193], v206 offset:36864
	ds_read_b128 v[194:197], v206 offset:37888
	ds_read_b128 v[198:201], v206 offset:38912
	ds_read_b128 v[212:215], v206 offset:39936
	global_load_lds_dwordx4 v154, s[22:23]
	s_mov_b32 m0, s62
	s_nop 0
	global_load_lds_dwordx4 v156, s[22:23]
	s_waitcnt vmcnt(8) lgkmcnt(0)
	s_barrier
	s_setprio 1
	v_mfma_f32_16x16x32_bf16 v[142:145], v[50:53], v[174:177], v[142:145]
	v_mfma_f32_16x16x32_bf16 v[138:141], v[66:69], v[174:177], v[138:141]
	v_mfma_f32_16x16x32_bf16 v[126:129], v[50:53], v[182:185], v[126:129]
	v_mfma_f32_16x16x32_bf16 v[122:125], v[66:69], v[182:185], v[122:125]
	v_mfma_f32_16x16x32_bf16 v[110:113], v[50:53], v[190:193], v[110:113]
	v_mfma_f32_16x16x32_bf16 v[106:109], v[66:69], v[190:193], v[106:109]
	v_mfma_f32_16x16x32_bf16 v[94:97], v[50:53], v[198:201], v[94:97]
	v_mfma_f32_16x16x32_bf16 v[90:93], v[66:69], v[198:201], v[90:93]
	v_mfma_f32_16x16x32_bf16 v[142:145], v[54:57], v[178:181], v[142:145]
	v_mfma_f32_16x16x32_bf16 v[138:141], v[70:73], v[178:181], v[138:141]
	v_mfma_f32_16x16x32_bf16 v[126:129], v[54:57], v[186:189], v[126:129]
	v_mfma_f32_16x16x32_bf16 v[122:125], v[70:73], v[186:189], v[122:125]
	v_mfma_f32_16x16x32_bf16 v[110:113], v[54:57], v[194:197], v[110:113]
	v_mfma_f32_16x16x32_bf16 v[106:109], v[70:73], v[194:197], v[106:109]
	v_mfma_f32_16x16x32_bf16 v[94:97], v[54:57], v[212:215], v[94:97]
	v_mfma_f32_16x16x32_bf16 v[90:93], v[70:73], v[212:215], v[90:93]
	s_setprio 0
	s_setprio 1
	v_mfma_f32_16x16x32_bf16 v[134:137], v[146:149], v[174:177], v[134:137]
	v_mfma_f32_16x16x32_bf16 v[130:133], v[166:169], v[174:177], v[130:133]
	v_mfma_f32_16x16x32_bf16 v[118:121], v[146:149], v[182:185], v[118:121]
	v_mfma_f32_16x16x32_bf16 v[114:117], v[166:169], v[182:185], v[114:117]
	v_mfma_f32_16x16x32_bf16 v[102:105], v[146:149], v[190:193], v[102:105]
	v_mfma_f32_16x16x32_bf16 v[98:101], v[166:169], v[190:193], v[98:101]
	v_mfma_f32_16x16x32_bf16 v[86:89], v[146:149], v[198:201], v[86:89]
	v_mfma_f32_16x16x32_bf16 v[82:85], v[166:169], v[198:201], v[82:85]
	v_mfma_f32_16x16x32_bf16 v[134:137], v[150:153], v[178:181], v[134:137]
	v_mfma_f32_16x16x32_bf16 v[130:133], v[170:173], v[178:181], v[130:133]
	v_mfma_f32_16x16x32_bf16 v[118:121], v[150:153], v[186:189], v[118:121]
	v_mfma_f32_16x16x32_bf16 v[114:117], v[170:173], v[186:189], v[114:117]
	v_mfma_f32_16x16x32_bf16 v[102:105], v[150:153], v[194:197], v[102:105]
	v_mfma_f32_16x16x32_bf16 v[98:101], v[170:173], v[194:197], v[98:101]
	v_mfma_f32_16x16x32_bf16 v[86:89], v[150:153], v[212:215], v[86:89]
	v_mfma_f32_16x16x32_bf16 v[82:85], v[170:173], v[212:215], v[82:85]
	s_setprio 0
	s_barrier
	s_add_u32 s22, s16, 0x8000
	s_addc_u32 s23, s17, 0
	s_add_i32 s51, s51, s58
	s_mov_b32 m0, s51
	ds_read_b128 v[174:177], v206 offset:49152
	ds_read_b128 v[178:181], v206 offset:50176
	ds_read_b128 v[182:185], v206 offset:51200
	ds_read_b128 v[186:189], v206 offset:52224
	ds_read_b128 v[190:193], v206 offset:53248
	ds_read_b128 v[194:197], v206 offset:54272
	ds_read_b128 v[198:201], v206 offset:55296
	ds_read_b128 v[212:215], v206 offset:56320
	global_load_lds_dwordx4 v154, s[22:23]
	s_add_i32 m0, s51, 0x2000
	s_add_u32 s16, s16, 0xc000
	s_addc_u32 s17, s17, 0
	global_load_lds_dwordx4 v156, s[22:23]
	s_add_i32 s22, s52, s58
	s_mov_b32 m0, s22
	s_nop 0
	global_load_lds_dwordx4 v154, s[16:17]
	s_add_i32 m0, s22, 0x2000
	s_nop 0
	global_load_lds_dwordx4 v156, s[16:17]
	s_mov_b32 m0, s72
	s_nop 0
	global_load_lds_dwordx4 v154, s[14:15]
	s_mov_b32 m0, s73
	s_nop 0
	global_load_lds_dwordx4 v156, s[14:15]
	s_waitcnt vmcnt(8) lgkmcnt(0)
	s_barrier
	s_setprio 1
	v_mfma_f32_16x16x32_bf16 v[78:81], v[50:53], v[174:177], v[78:81]
	v_mfma_f32_16x16x32_bf16 v[74:77], v[66:69], v[174:177], v[74:77]
	v_mfma_f32_16x16x32_bf16 v[62:65], v[50:53], v[182:185], v[62:65]
	v_mfma_f32_16x16x32_bf16 v[58:61], v[66:69], v[182:185], v[58:61]
	v_mfma_f32_16x16x32_bf16 v[30:33], v[50:53], v[190:193], v[30:33]
	v_mfma_f32_16x16x32_bf16 v[26:29], v[66:69], v[190:193], v[26:29]
	v_mfma_f32_16x16x32_bf16 v[14:17], v[50:53], v[198:201], v[14:17]
	v_mfma_f32_16x16x32_bf16 v[10:13], v[66:69], v[198:201], v[10:13]
	v_mfma_f32_16x16x32_bf16 v[78:81], v[54:57], v[178:181], v[78:81]
	v_mfma_f32_16x16x32_bf16 v[74:77], v[70:73], v[178:181], v[74:77]
	v_mfma_f32_16x16x32_bf16 v[62:65], v[54:57], v[186:189], v[62:65]
	v_mfma_f32_16x16x32_bf16 v[58:61], v[70:73], v[186:189], v[58:61]
	v_mfma_f32_16x16x32_bf16 v[30:33], v[54:57], v[194:197], v[30:33]
	v_mfma_f32_16x16x32_bf16 v[26:29], v[70:73], v[194:197], v[26:29]
	v_mfma_f32_16x16x32_bf16 v[14:17], v[54:57], v[212:215], v[14:17]
	v_mfma_f32_16x16x32_bf16 v[10:13], v[70:73], v[212:215], v[10:13]
	s_setprio 0
	s_setprio 1
	v_mfma_f32_16x16x32_bf16 v[38:41], v[146:149], v[174:177], v[38:41]
	v_mfma_f32_16x16x32_bf16 v[70:73], v[150:153], v[178:181], v[38:41]
	v_mfma_f32_16x16x32_bf16 v[38:41], v[166:169], v[174:177], v[42:45]
	v_mfma_f32_16x16x32_bf16 v[66:69], v[170:173], v[178:181], v[38:41]
	v_mfma_f32_16x16x32_bf16 v[38:41], v[146:149], v[182:185], v[46:49]
	v_mfma_f32_16x16x32_bf16 v[34:37], v[166:169], v[182:185], v[34:37]
	v_mfma_f32_16x16x32_bf16 v[22:25], v[146:149], v[190:193], v[22:25]
	v_mfma_f32_16x16x32_bf16 v[18:21], v[166:169], v[190:193], v[18:21]
	v_mfma_f32_16x16x32_bf16 v[6:9], v[146:149], v[198:201], v[6:9]
	v_mfma_f32_16x16x32_bf16 v[2:5], v[166:169], v[198:201], v[2:5]
	v_mfma_f32_16x16x32_bf16 v[46:49], v[150:153], v[186:189], v[38:41]
	v_mfma_f32_16x16x32_bf16 v[34:37], v[170:173], v[186:189], v[34:37]
	v_mfma_f32_16x16x32_bf16 v[22:25], v[150:153], v[194:197], v[22:25]
	v_mfma_f32_16x16x32_bf16 v[18:21], v[170:173], v[194:197], v[18:21]
	v_mfma_f32_16x16x32_bf16 v[6:9], v[150:153], v[212:215], v[6:9]
	v_mfma_f32_16x16x32_bf16 v[2:5], v[170:173], v[212:215], v[2:5]
	s_setprio 0
	s_barrier
	s_add_i32 s50, s50, 2
	s_add_u32 s41, s41, 0x10000
	s_addc_u32 s43, s43, 0
	s_add_u32 s12, s12, 0x10000
	s_addc_u32 s13, s13, 0
	s_cmp_gt_u32 s50, 29
	s_cbranch_scc0 .LBB0_304
	s_and_b64 vcc, exec, s[26:27]
	s_cbranch_vccz .LBB0_307
	s_barrier

.LBB0_1111:
	s_add_u32 s14, s12, 0x4000
	s_addc_u32 s15, s13, 0
	s_cmp_eq_u32 s66, 28
	s_cselect_b32 s22, s42, s14
	s_cselect_b32 s23, s43, s15
	s_cselect_b32 s16, s44, s31
	s_cselect_b32 s17, s45, s41
	s_add_u32 s14, s22, 0x8000
	s_addc_u32 s15, s23, 0
	s_add_i32 s67, 0, 0x10000
	s_add_i32 s70, 0, 0x14000
	ds_read_b128 v[42:45], v229
	ds_read_b128 v[46:49], v229 offset:1024
	ds_read_b128 v[50:53], v229 offset:2048
	ds_read_b128 v[54:57], v229 offset:3072
	ds_read_b128 v[66:69], v229 offset:16384
	ds_read_b128 v[70:73], v229 offset:17408
	ds_read_b128 v[74:77], v229 offset:18432
	ds_read_b128 v[78:81], v229 offset:19456
	s_add_i32 m0, s50, 0xc000
	ds_read_b128 v[162:165], v205
	ds_read_b128 v[166:169], v205 offset:1024
	ds_read_b128 v[170:173], v205 offset:2048
	ds_read_b128 v[174:177], v205 offset:3072
	ds_read_b128 v[178:181], v205 offset:4096
	ds_read_b128 v[182:185], v205 offset:5120
	ds_read_b128 v[192:195], v205 offset:6144
	ds_read_b128 v[196:199], v205 offset:7168
	global_load_lds_dwordx4 v186, s[12:13]
	s_add_i32 m0, s50, 0xe000
	s_nop 0
	global_load_lds_dwordx4 v188, s[12:13]
	s_waitcnt vmcnt(8) lgkmcnt(0)
	s_barrier
	s_setprio 1
	v_mfma_f32_16x16x32_bf16 v[158:161], v[42:45], v[162:165], v[158:161]
	v_mfma_f32_16x16x32_bf16 v[154:157], v[50:53], v[162:165], v[154:157]
	v_mfma_f32_16x16x32_bf16 v[142:145], v[42:45], v[170:173], v[142:145]
	v_mfma_f32_16x16x32_bf16 v[138:141], v[50:53], v[170:173], v[138:141]
	v_mfma_f32_16x16x32_bf16 v[126:129], v[42:45], v[178:181], v[126:129]
	v_mfma_f32_16x16x32_bf16 v[122:125], v[50:53], v[178:181], v[122:125]
	v_mfma_f32_16x16x32_bf16 v[110:113], v[42:45], v[192:195], v[110:113]
	v_mfma_f32_16x16x32_bf16 v[106:109], v[50:53], v[192:195], v[106:109]
	v_mfma_f32_16x16x32_bf16 v[158:161], v[46:49], v[166:169], v[158:161]
	v_mfma_f32_16x16x32_bf16 v[154:157], v[54:57], v[166:169], v[154:157]
	v_mfma_f32_16x16x32_bf16 v[142:145], v[46:49], v[174:177], v[142:145]
	v_mfma_f32_16x16x32_bf16 v[138:141], v[54:57], v[174:177], v[138:141]
	v_mfma_f32_16x16x32_bf16 v[126:129], v[46:49], v[182:185], v[126:129]
	v_mfma_f32_16x16x32_bf16 v[122:125], v[54:57], v[182:185], v[122:125]
	v_mfma_f32_16x16x32_bf16 v[110:113], v[46:49], v[196:199], v[110:113]
	v_mfma_f32_16x16x32_bf16 v[106:109], v[54:57], v[196:199], v[106:109]
	s_setprio 0
	s_setprio 1
	v_mfma_f32_16x16x32_bf16 v[150:153], v[66:69], v[162:165], v[150:153]
	v_mfma_f32_16x16x32_bf16 v[146:149], v[74:77], v[162:165], v[146:149]
	v_mfma_f32_16x16x32_bf16 v[134:137], v[66:69], v[170:173], v[134:137]
	v_mfma_f32_16x16x32_bf16 v[130:133], v[74:77], v[170:173], v[130:133]
	v_mfma_f32_16x16x32_bf16 v[118:121], v[66:69], v[178:181], v[118:121]
	v_mfma_f32_16x16x32_bf16 v[114:117], v[74:77], v[178:181], v[114:117]
	v_mfma_f32_16x16x32_bf16 v[102:105], v[66:69], v[192:195], v[102:105]
	v_mfma_f32_16x16x32_bf16 v[98:101], v[74:77], v[192:195], v[98:101]
	v_mfma_f32_16x16x32_bf16 v[150:153], v[70:73], v[166:169], v[150:153]
	v_mfma_f32_16x16x32_bf16 v[146:149], v[78:81], v[166:169], v[146:149]
	v_mfma_f32_16x16x32_bf16 v[134:137], v[70:73], v[174:177], v[134:137]
	v_mfma_f32_16x16x32_bf16 v[130:133], v[78:81], v[174:177], v[130:133]
	v_mfma_f32_16x16x32_bf16 v[118:121], v[70:73], v[182:185], v[118:121]
	v_mfma_f32_16x16x32_bf16 v[114:117], v[78:81], v[182:185], v[114:117]
	v_mfma_f32_16x16x32_bf16 v[102:105], v[70:73], v[196:199], v[102:105]
	v_mfma_f32_16x16x32_bf16 v[98:101], v[78:81], v[196:199], v[98:101]
	s_setprio 0
	s_barrier
	s_add_i32 s67, s67, s49
	s_mov_b32 m0, s67
	ds_read_b128 v[162:165], v205 offset:16384
	ds_read_b128 v[166:169], v205 offset:17408
	ds_read_b128 v[170:173], v205 offset:18432
	ds_read_b128 v[174:177], v205 offset:19456
	ds_read_b128 v[178:181], v205 offset:20480
	ds_read_b128 v[182:185], v205 offset:21504
	ds_read_b128 v[192:195], v205 offset:22528
	ds_read_b128 v[196:199], v205 offset:23552
	global_load_lds_dwordx4 v186, s[16:17]
	s_add_i32 m0, s67, 0x2000
	s_add_u32 s68, s16, 0x4000
	s_addc_u32 s69, s17, 0
	s_add_i32 s67, s70, s49
	global_load_lds_dwordx4 v188, s[16:17]
	s_mov_b32 m0, s67
	s_nop 0
	global_load_lds_dwordx4 v186, s[68:69]
	s_add_i32 m0, s67, 0x2000
	s_nop 0
	global_load_lds_dwordx4 v188, s[68:69]
	s_mov_b32 m0, s50
	s_nop 0
	global_load_lds_dwordx4 v186, s[22:23]
	s_mov_b32 m0, s51
	s_nop 0
	global_load_lds_dwordx4 v188, s[22:23]
	s_waitcnt vmcnt(8) lgkmcnt(0)
	s_barrier
	s_setprio 1
	v_mfma_f32_16x16x32_bf16 v[94:97], v[42:45], v[162:165], v[94:97]
	v_mfma_f32_16x16x32_bf16 v[90:93], v[50:53], v[162:165], v[90:93]
	v_mfma_f32_16x16x32_bf16 v[62:65], v[42:45], v[170:173], v[62:65]
	v_mfma_f32_16x16x32_bf16 v[58:61], v[50:53], v[170:173], v[58:61]
	v_mfma_f32_16x16x32_bf16 v[30:33], v[42:45], v[178:181], v[30:33]
	v_mfma_f32_16x16x32_bf16 v[26:29], v[50:53], v[178:181], v[26:29]
	v_mfma_f32_16x16x32_bf16 v[14:17], v[42:45], v[192:195], v[14:17]
	v_mfma_f32_16x16x32_bf16 v[10:13], v[50:53], v[192:195], v[10:13]
	v_mfma_f32_16x16x32_bf16 v[94:97], v[46:49], v[166:169], v[94:97]
	v_mfma_f32_16x16x32_bf16 v[90:93], v[54:57], v[166:169], v[90:93]
	v_mfma_f32_16x16x32_bf16 v[62:65], v[46:49], v[174:177], v[62:65]
	v_mfma_f32_16x16x32_bf16 v[58:61], v[54:57], v[174:177], v[58:61]
	v_mfma_f32_16x16x32_bf16 v[30:33], v[46:49], v[182:185], v[30:33]
	v_mfma_f32_16x16x32_bf16 v[26:29], v[54:57], v[182:185], v[26:29]
	v_mfma_f32_16x16x32_bf16 v[14:17], v[46:49], v[196:199], v[14:17]
	v_mfma_f32_16x16x32_bf16 v[10:13], v[54:57], v[196:199], v[10:13]
	s_setprio 0
	s_setprio 1
	v_mfma_f32_16x16x32_bf16 v[38:41], v[66:69], v[170:173], v[38:41]
	v_mfma_f32_16x16x32_bf16 v[34:37], v[74:77], v[170:173], v[34:37]
	v_mfma_f32_16x16x32_bf16 v[22:25], v[66:69], v[178:181], v[22:25]
	v_mfma_f32_16x16x32_bf16 v[18:21], v[74:77], v[178:181], v[18:21]
	v_mfma_f32_16x16x32_bf16 v[6:9], v[66:69], v[192:195], v[6:9]
	v_mfma_f32_16x16x32_bf16 v[2:5], v[74:77], v[192:195], v[2:5]
	v_mfma_f32_16x16x32_bf16 v[42:45], v[66:69], v[162:165], v[86:89]
	v_mfma_f32_16x16x32_bf16 v[46:49], v[74:77], v[162:165], v[82:85]
	v_mfma_f32_16x16x32_bf16 v[38:41], v[70:73], v[174:177], v[38:41]
	v_mfma_f32_16x16x32_bf16 v[34:37], v[78:81], v[174:177], v[34:37]
	v_mfma_f32_16x16x32_bf16 v[22:25], v[70:73], v[182:185], v[22:25]
	v_mfma_f32_16x16x32_bf16 v[18:21], v[78:81], v[182:185], v[18:21]
	v_mfma_f32_16x16x32_bf16 v[6:9], v[70:73], v[196:199], v[6:9]
	v_mfma_f32_16x16x32_bf16 v[2:5], v[78:81], v[196:199], v[2:5]
	v_mfma_f32_16x16x32_bf16 v[42:45], v[70:73], v[166:169], v[42:45]
	v_mfma_f32_16x16x32_bf16 v[46:49], v[78:81], v[166:169], v[46:49]
	s_setprio 0
	s_barrier
	s_add_i32 s67, 0, 0x18000
	s_add_i32 s68, 0, 0x1c000
	ds_read_b128 v[50:53], v229 offset:32768
	ds_read_b128 v[54:57], v229 offset:33792
	ds_read_b128 v[66:69], v229 offset:34816
	ds_read_b128 v[70:73], v229 offset:35840
	ds_read_b128 v[74:77], v229 offset:49152
	ds_read_b128 v[78:81], v229 offset:50176
	ds_read_b128 v[162:165], v229 offset:51200
	ds_read_b128 v[166:169], v229 offset:52224
	s_add_u32 s22, s22, 0x4000
	s_addc_u32 s23, s23, 0
	s_mov_b32 m0, s52
	ds_read_b128 v[82:85], v205 offset:32768
	ds_read_b128 v[86:89], v205 offset:33792
	ds_read_b128 v[170:173], v205 offset:34816
	ds_read_b128 v[174:177], v205 offset:35840
	ds_read_b128 v[178:181], v205 offset:36864
	ds_read_b128 v[182:185], v205 offset:37888
	ds_read_b128 v[192:195], v205 offset:38912
	ds_read_b128 v[196:199], v205 offset:39936
	global_load_lds_dwordx4 v186, s[22:23]
	s_mov_b32 m0, s53
	s_nop 0
	global_load_lds_dwordx4 v188, s[22:23]
	s_waitcnt vmcnt(8) lgkmcnt(0)
	s_barrier
	s_setprio 1
	v_mfma_f32_16x16x32_bf16 v[158:161], v[50:53], v[82:85], v[158:161]
	v_mfma_f32_16x16x32_bf16 v[154:157], v[66:69], v[82:85], v[154:157]
	v_mfma_f32_16x16x32_bf16 v[142:145], v[50:53], v[170:173], v[142:145]
	v_mfma_f32_16x16x32_bf16 v[138:141], v[66:69], v[170:173], v[138:141]
	v_mfma_f32_16x16x32_bf16 v[126:129], v[50:53], v[178:181], v[126:129]
	v_mfma_f32_16x16x32_bf16 v[122:125], v[66:69], v[178:181], v[122:125]
	v_mfma_f32_16x16x32_bf16 v[110:113], v[50:53], v[192:195], v[110:113]
	v_mfma_f32_16x16x32_bf16 v[106:109], v[66:69], v[192:195], v[106:109]
	v_mfma_f32_16x16x32_bf16 v[158:161], v[54:57], v[86:89], v[158:161]
	v_mfma_f32_16x16x32_bf16 v[154:157], v[70:73], v[86:89], v[154:157]
	v_mfma_f32_16x16x32_bf16 v[142:145], v[54:57], v[174:177], v[142:145]
	v_mfma_f32_16x16x32_bf16 v[138:141], v[70:73], v[174:177], v[138:141]
	v_mfma_f32_16x16x32_bf16 v[126:129], v[54:57], v[182:185], v[126:129]
	v_mfma_f32_16x16x32_bf16 v[122:125], v[70:73], v[182:185], v[122:125]
	v_mfma_f32_16x16x32_bf16 v[110:113], v[54:57], v[196:199], v[110:113]
	v_mfma_f32_16x16x32_bf16 v[106:109], v[70:73], v[196:199], v[106:109]
	s_setprio 0
	s_setprio 1
	v_mfma_f32_16x16x32_bf16 v[150:153], v[74:77], v[82:85], v[150:153]
	v_mfma_f32_16x16x32_bf16 v[82:85], v[162:165], v[82:85], v[146:149]
	v_mfma_f32_16x16x32_bf16 v[146:149], v[166:169], v[86:89], v[82:85]
	v_mfma_f32_16x16x32_bf16 v[82:85], v[74:77], v[170:173], v[134:137]
	v_mfma_f32_16x16x32_bf16 v[134:137], v[78:81], v[174:177], v[82:85]
	v_mfma_f32_16x16x32_bf16 v[82:85], v[162:165], v[170:173], v[130:133]
	v_mfma_f32_16x16x32_bf16 v[130:133], v[166:169], v[174:177], v[82:85]
	v_mfma_f32_16x16x32_bf16 v[82:85], v[74:77], v[178:181], v[118:121]
	v_mfma_f32_16x16x32_bf16 v[118:121], v[78:81], v[182:185], v[82:85]
	v_mfma_f32_16x16x32_bf16 v[82:85], v[162:165], v[178:181], v[114:117]
	v_mfma_f32_16x16x32_bf16 v[114:117], v[166:169], v[182:185], v[82:85]
	v_mfma_f32_16x16x32_bf16 v[82:85], v[74:77], v[192:195], v[102:105]
	v_mfma_f32_16x16x32_bf16 v[102:105], v[78:81], v[196:199], v[82:85]
	v_mfma_f32_16x16x32_bf16 v[82:85], v[162:165], v[192:195], v[98:101]
	v_mfma_f32_16x16x32_bf16 v[150:153], v[78:81], v[86:89], v[150:153]
	v_mfma_f32_16x16x32_bf16 v[98:101], v[166:169], v[196:199], v[82:85]
	s_setprio 0
	s_barrier
	s_add_u32 s22, s16, 0x8000
	s_addc_u32 s23, s17, 0
	s_add_i32 s67, s67, s49
	s_mov_b32 m0, s67
	ds_read_b128 v[82:85], v205 offset:49152
	ds_read_b128 v[170:173], v205 offset:50176
	ds_read_b128 v[174:177], v205 offset:51200
	ds_read_b128 v[178:181], v205 offset:52224
	ds_read_b128 v[182:185], v205 offset:53248
	ds_read_b128 v[192:195], v205 offset:54272
	ds_read_b128 v[196:199], v205 offset:55296
	ds_read_b128 v[212:215], v205 offset:56320
	global_load_lds_dwordx4 v186, s[22:23]
	s_add_i32 m0, s67, 0x2000
	s_add_u32 s16, s16, 0xc000
	s_addc_u32 s17, s17, 0
	global_load_lds_dwordx4 v188, s[22:23]
	s_add_i32 s22, s68, s49
	s_mov_b32 m0, s22
	s_nop 0
	global_load_lds_dwordx4 v186, s[16:17]
	s_add_i32 m0, s22, 0x2000
	s_nop 0
	global_load_lds_dwordx4 v188, s[16:17]
	s_mov_b32 m0, s60
	s_nop 0
	global_load_lds_dwordx4 v186, s[14:15]
	s_mov_b32 m0, s61
	s_nop 0
	global_load_lds_dwordx4 v188, s[14:15]
	s_waitcnt vmcnt(8) lgkmcnt(0)
	s_barrier
	s_setprio 1
	v_mfma_f32_16x16x32_bf16 v[86:89], v[50:53], v[82:85], v[94:97]
	v_mfma_f32_16x16x32_bf16 v[94:97], v[54:57], v[170:173], v[86:89]
	v_mfma_f32_16x16x32_bf16 v[86:89], v[66:69], v[82:85], v[90:93]
	v_mfma_f32_16x16x32_bf16 v[62:65], v[50:53], v[174:177], v[62:65]
	v_mfma_f32_16x16x32_bf16 v[58:61], v[66:69], v[174:177], v[58:61]
	v_mfma_f32_16x16x32_bf16 v[30:33], v[50:53], v[182:185], v[30:33]
	v_mfma_f32_16x16x32_bf16 v[26:29], v[66:69], v[182:185], v[26:29]
	v_mfma_f32_16x16x32_bf16 v[14:17], v[50:53], v[196:199], v[14:17]
	v_mfma_f32_16x16x32_bf16 v[10:13], v[66:69], v[196:199], v[10:13]
	v_mfma_f32_16x16x32_bf16 v[90:93], v[70:73], v[170:173], v[86:89]
	v_mfma_f32_16x16x32_bf16 v[62:65], v[54:57], v[178:181], v[62:65]
	v_mfma_f32_16x16x32_bf16 v[58:61], v[70:73], v[178:181], v[58:61]
	v_mfma_f32_16x16x32_bf16 v[30:33], v[54:57], v[192:195], v[30:33]
	v_mfma_f32_16x16x32_bf16 v[26:29], v[70:73], v[192:195], v[26:29]
	v_mfma_f32_16x16x32_bf16 v[14:17], v[54:57], v[212:215], v[14:17]
	v_mfma_f32_16x16x32_bf16 v[10:13], v[70:73], v[212:215], v[10:13]
	s_setprio 0
	s_setprio 1
	v_mfma_f32_16x16x32_bf16 v[42:45], v[74:77], v[82:85], v[42:45]
	v_mfma_f32_16x16x32_bf16 v[86:89], v[78:81], v[170:173], v[42:45]
	v_mfma_f32_16x16x32_bf16 v[42:45], v[162:165], v[82:85], v[46:49]
	v_mfma_f32_16x16x32_bf16 v[38:41], v[74:77], v[174:177], v[38:41]
	v_mfma_f32_16x16x32_bf16 v[34:37], v[162:165], v[174:177], v[34:37]
	v_mfma_f32_16x16x32_bf16 v[22:25], v[74:77], v[182:185], v[22:25]
	v_mfma_f32_16x16x32_bf16 v[18:21], v[162:165], v[182:185], v[18:21]
	v_mfma_f32_16x16x32_bf16 v[6:9], v[74:77], v[196:199], v[6:9]
	v_mfma_f32_16x16x32_bf16 v[2:5], v[162:165], v[196:199], v[2:5]
	v_mfma_f32_16x16x32_bf16 v[82:85], v[166:169], v[170:173], v[42:45]
	v_mfma_f32_16x16x32_bf16 v[38:41], v[78:81], v[178:181], v[38:41]
	v_mfma_f32_16x16x32_bf16 v[34:37], v[166:169], v[178:181], v[34:37]
	v_mfma_f32_16x16x32_bf16 v[22:25], v[78:81], v[192:195], v[22:25]
	v_mfma_f32_16x16x32_bf16 v[18:21], v[166:169], v[192:195], v[18:21]
	v_mfma_f32_16x16x32_bf16 v[6:9], v[78:81], v[212:215], v[6:9]
	v_mfma_f32_16x16x32_bf16 v[2:5], v[166:169], v[212:215], v[2:5]
	s_setprio 0
	s_barrier
	s_add_i32 s66, s66, 2
	s_add_u32 s12, s12, 0x10000
	s_addc_u32 s13, s13, 0
	s_add_u32 s31, s31, 0x10000
	s_addc_u32 s41, s41, 0
	s_cmp_gt_u32 s66, 29
	s_cbranch_scc0 .LBB0_1111
	s_and_b64 vcc, exec, s[24:25]
	s_cbranch_vccz .LBB0_1114
	s_barrier

.LBB0_1196:
	s_add_u32 s16, s14, 1
	s_addc_u32 s17, s15, 0
	s_lshl_b64 s[16:17], s[16:17], s60
	s_add_u32 s16, s12, s16
	s_addc_u32 s17, s13, s17
	s_cmp_eq_u32 s14, 31
	s_cselect_b32 s46, s42, s16
	s_cselect_b32 s47, s43, s17
	s_cselect_b32 s22, s44, s73
	s_cselect_b32 s23, s45, s74
	s_add_u32 s16, s46, s59
	s_addc_u32 s17, s47, 0
	s_add_i32 s75, 0, 0x10000
	s_add_i32 s78, 0, 0x14000
	ds_read_b128 v[66:69], v229
	ds_read_b128 v[70:73], v229 offset:1024
	ds_read_b128 v[74:77], v229 offset:2048
	ds_read_b128 v[78:81], v229 offset:3072
	ds_read_b128 v[164:167], v229 offset:16384
	ds_read_b128 v[168:171], v229 offset:17408
	ds_read_b128 v[172:175], v229 offset:18432
	ds_read_b128 v[176:179], v229 offset:19456
	s_lshl_b64 s[76:77], s[14:15], s60
	s_add_u32 s76, s31, s76
	s_addc_u32 s77, s41, s77
	s_add_i32 m0, s54, 0xc000
	ds_read_b128 v[180:183], v161
	ds_read_b128 v[184:187], v161 offset:1024
	ds_read_b128 v[188:191], v161 offset:2048
	ds_read_b128 v[192:195], v161 offset:3072
	ds_read_b128 v[196:199], v161 offset:4096
	ds_read_b128 v[200:203], v161 offset:5120
	ds_read_b128 v[204:207], v161 offset:6144
	ds_read_b128 v[212:215], v161 offset:7168
	global_load_lds_dwordx4 v152, s[76:77]
	s_add_i32 m0, s54, 0xe000
	s_nop 0
	global_load_lds_dwordx4 v150, s[76:77]
	s_waitcnt vmcnt(8) lgkmcnt(0)
	s_barrier
	s_setprio 1
	v_mfma_f32_16x16x32_bf16 v[142:145], v[66:69], v[180:183], v[142:145]
	v_mfma_f32_16x16x32_bf16 v[138:141], v[74:77], v[180:183], v[138:141]
	v_mfma_f32_16x16x32_bf16 v[126:129], v[66:69], v[188:191], v[126:129]
	v_mfma_f32_16x16x32_bf16 v[122:125], v[74:77], v[188:191], v[122:125]
	v_mfma_f32_16x16x32_bf16 v[110:113], v[66:69], v[196:199], v[110:113]
	v_mfma_f32_16x16x32_bf16 v[106:109], v[74:77], v[196:199], v[106:109]
	v_mfma_f32_16x16x32_bf16 v[94:97], v[66:69], v[204:207], v[94:97]
	v_mfma_f32_16x16x32_bf16 v[90:93], v[74:77], v[204:207], v[90:93]
	v_mfma_f32_16x16x32_bf16 v[142:145], v[70:73], v[184:187], v[142:145]
	v_mfma_f32_16x16x32_bf16 v[138:141], v[78:81], v[184:187], v[138:141]
	v_mfma_f32_16x16x32_bf16 v[126:129], v[70:73], v[192:195], v[126:129]
	v_mfma_f32_16x16x32_bf16 v[122:125], v[78:81], v[192:195], v[122:125]
	v_mfma_f32_16x16x32_bf16 v[110:113], v[70:73], v[200:203], v[110:113]
	v_mfma_f32_16x16x32_bf16 v[106:109], v[78:81], v[200:203], v[106:109]
	v_mfma_f32_16x16x32_bf16 v[94:97], v[70:73], v[212:215], v[94:97]
	v_mfma_f32_16x16x32_bf16 v[90:93], v[78:81], v[212:215], v[90:93]
	s_setprio 0
	s_setprio 1
	v_mfma_f32_16x16x32_bf16 v[134:137], v[164:167], v[180:183], v[134:137]
	v_mfma_f32_16x16x32_bf16 v[130:133], v[172:175], v[180:183], v[130:133]
	v_mfma_f32_16x16x32_bf16 v[118:121], v[164:167], v[188:191], v[118:121]
	v_mfma_f32_16x16x32_bf16 v[114:117], v[172:175], v[188:191], v[114:117]
	v_mfma_f32_16x16x32_bf16 v[102:105], v[164:167], v[196:199], v[102:105]
	v_mfma_f32_16x16x32_bf16 v[98:101], v[172:175], v[196:199], v[98:101]
	v_mfma_f32_16x16x32_bf16 v[86:89], v[164:167], v[204:207], v[86:89]
	v_mfma_f32_16x16x32_bf16 v[82:85], v[172:175], v[204:207], v[82:85]
	v_mfma_f32_16x16x32_bf16 v[134:137], v[168:171], v[184:187], v[134:137]
	v_mfma_f32_16x16x32_bf16 v[130:133], v[176:179], v[184:187], v[130:133]
	v_mfma_f32_16x16x32_bf16 v[118:121], v[168:171], v[192:195], v[118:121]
	v_mfma_f32_16x16x32_bf16 v[114:117], v[176:179], v[192:195], v[114:117]
	v_mfma_f32_16x16x32_bf16 v[102:105], v[168:171], v[200:203], v[102:105]
	v_mfma_f32_16x16x32_bf16 v[98:101], v[176:179], v[200:203], v[98:101]
	v_mfma_f32_16x16x32_bf16 v[86:89], v[168:171], v[212:215], v[86:89]
	v_mfma_f32_16x16x32_bf16 v[82:85], v[176:179], v[212:215], v[82:85]
	s_setprio 0
	s_barrier
	s_add_i32 s75, s75, s53
	s_mov_b32 m0, s75
	ds_read_b128 v[180:183], v161 offset:16384
	ds_read_b128 v[184:187], v161 offset:17408
	ds_read_b128 v[188:191], v161 offset:18432
	ds_read_b128 v[192:195], v161 offset:19456
	ds_read_b128 v[196:199], v161 offset:20480
	ds_read_b128 v[200:203], v161 offset:21504
	ds_read_b128 v[204:207], v161 offset:22528
	ds_read_b128 v[212:215], v161 offset:23552
	global_load_lds_dwordx4 v146, s[22:23]
	s_add_i32 m0, s75, 0x2000
	s_add_u32 s76, s22, 0x4000
	s_addc_u32 s77, s23, 0
	s_add_i32 s75, s78, s53
	global_load_lds_dwordx4 v148, s[22:23]
	s_mov_b32 m0, s75
	s_nop 0
	global_load_lds_dwordx4 v146, s[76:77]
	s_add_i32 m0, s75, 0x2000
	s_nop 0
	global_load_lds_dwordx4 v148, s[76:77]
	s_mov_b32 m0, s54
	s_nop 0
	global_load_lds_dwordx4 v152, s[46:47]
	s_mov_b32 m0, s55
	s_nop 0
	global_load_lds_dwordx4 v150, s[46:47]
	s_waitcnt vmcnt(8) lgkmcnt(0)
	s_barrier
	s_setprio 1
	v_mfma_f32_16x16x32_bf16 v[62:65], v[66:69], v[180:183], v[62:65]
	v_mfma_f32_16x16x32_bf16 v[58:61], v[74:77], v[180:183], v[58:61]
	v_mfma_f32_16x16x32_bf16 v[46:49], v[66:69], v[188:191], v[46:49]
	v_mfma_f32_16x16x32_bf16 v[42:45], v[74:77], v[188:191], v[42:45]
	v_mfma_f32_16x16x32_bf16 v[30:33], v[66:69], v[196:199], v[30:33]
	v_mfma_f32_16x16x32_bf16 v[26:29], v[74:77], v[196:199], v[26:29]
	v_mfma_f32_16x16x32_bf16 v[14:17], v[66:69], v[204:207], v[14:17]
	v_mfma_f32_16x16x32_bf16 v[10:13], v[74:77], v[204:207], v[10:13]
	v_mfma_f32_16x16x32_bf16 v[62:65], v[70:73], v[184:187], v[62:65]
	v_mfma_f32_16x16x32_bf16 v[58:61], v[78:81], v[184:187], v[58:61]
	v_mfma_f32_16x16x32_bf16 v[46:49], v[70:73], v[192:195], v[46:49]
	v_mfma_f32_16x16x32_bf16 v[42:45], v[78:81], v[192:195], v[42:45]
	v_mfma_f32_16x16x32_bf16 v[30:33], v[70:73], v[200:203], v[30:33]
	v_mfma_f32_16x16x32_bf16 v[26:29], v[78:81], v[200:203], v[26:29]
	v_mfma_f32_16x16x32_bf16 v[14:17], v[70:73], v[212:215], v[14:17]
	v_mfma_f32_16x16x32_bf16 v[10:13], v[78:81], v[212:215], v[10:13]
	s_setprio 0
	s_setprio 1
	v_mfma_f32_16x16x32_bf16 v[54:57], v[164:167], v[180:183], v[54:57]
	v_mfma_f32_16x16x32_bf16 v[50:53], v[172:175], v[180:183], v[50:53]
	v_mfma_f32_16x16x32_bf16 v[38:41], v[164:167], v[188:191], v[38:41]
	v_mfma_f32_16x16x32_bf16 v[34:37], v[172:175], v[188:191], v[34:37]
	v_mfma_f32_16x16x32_bf16 v[22:25], v[164:167], v[196:199], v[22:25]
	v_mfma_f32_16x16x32_bf16 v[18:21], v[172:175], v[196:199], v[18:21]
	v_mfma_f32_16x16x32_bf16 v[6:9], v[164:167], v[204:207], v[6:9]
	v_mfma_f32_16x16x32_bf16 v[2:5], v[172:175], v[204:207], v[2:5]
	v_mfma_f32_16x16x32_bf16 v[54:57], v[168:171], v[184:187], v[54:57]
	v_mfma_f32_16x16x32_bf16 v[50:53], v[176:179], v[184:187], v[50:53]
	v_mfma_f32_16x16x32_bf16 v[38:41], v[168:171], v[192:195], v[38:41]
	v_mfma_f32_16x16x32_bf16 v[34:37], v[176:179], v[192:195], v[34:37]
	v_mfma_f32_16x16x32_bf16 v[22:25], v[168:171], v[200:203], v[22:25]
	v_mfma_f32_16x16x32_bf16 v[18:21], v[176:179], v[200:203], v[18:21]
	v_mfma_f32_16x16x32_bf16 v[6:9], v[168:171], v[212:215], v[6:9]
	v_mfma_f32_16x16x32_bf16 v[2:5], v[176:179], v[212:215], v[2:5]
	s_setprio 0
	s_barrier
	s_add_i32 s75, 0, 0x18000
	s_add_i32 s76, 0, 0x1c000
	ds_read_b128 v[66:69], v229 offset:32768
	ds_read_b128 v[70:73], v229 offset:33792
	ds_read_b128 v[74:77], v229 offset:34816
	ds_read_b128 v[78:81], v229 offset:35840
	ds_read_b128 v[164:167], v229 offset:49152
	ds_read_b128 v[168:171], v229 offset:50176
	ds_read_b128 v[172:175], v229 offset:51200
	ds_read_b128 v[176:179], v229 offset:52224
	s_add_u32 s46, s46, s52
	s_addc_u32 s47, s47, 0
	s_mov_b32 m0, s56
	ds_read_b128 v[180:183], v161 offset:32768
	ds_read_b128 v[184:187], v161 offset:33792
	ds_read_b128 v[188:191], v161 offset:34816
	ds_read_b128 v[192:195], v161 offset:35840
	ds_read_b128 v[196:199], v161 offset:36864
	ds_read_b128 v[200:203], v161 offset:37888
	ds_read_b128 v[204:207], v161 offset:38912
	ds_read_b128 v[212:215], v161 offset:39936
	global_load_lds_dwordx4 v152, s[46:47]
	s_mov_b32 m0, s57
	s_nop 0
	global_load_lds_dwordx4 v150, s[46:47]
	s_waitcnt vmcnt(8) lgkmcnt(0)
	s_barrier
	s_setprio 1
	v_mfma_f32_16x16x32_bf16 v[142:145], v[66:69], v[180:183], v[142:145]
	v_mfma_f32_16x16x32_bf16 v[138:141], v[74:77], v[180:183], v[138:141]
	v_mfma_f32_16x16x32_bf16 v[126:129], v[66:69], v[188:191], v[126:129]
	v_mfma_f32_16x16x32_bf16 v[122:125], v[74:77], v[188:191], v[122:125]
	v_mfma_f32_16x16x32_bf16 v[110:113], v[66:69], v[196:199], v[110:113]
	v_mfma_f32_16x16x32_bf16 v[106:109], v[74:77], v[196:199], v[106:109]
	v_mfma_f32_16x16x32_bf16 v[94:97], v[66:69], v[204:207], v[94:97]
	v_mfma_f32_16x16x32_bf16 v[90:93], v[74:77], v[204:207], v[90:93]
	v_mfma_f32_16x16x32_bf16 v[142:145], v[70:73], v[184:187], v[142:145]
	v_mfma_f32_16x16x32_bf16 v[138:141], v[78:81], v[184:187], v[138:141]
	v_mfma_f32_16x16x32_bf16 v[126:129], v[70:73], v[192:195], v[126:129]
	v_mfma_f32_16x16x32_bf16 v[122:125], v[78:81], v[192:195], v[122:125]
	v_mfma_f32_16x16x32_bf16 v[110:113], v[70:73], v[200:203], v[110:113]
	v_mfma_f32_16x16x32_bf16 v[106:109], v[78:81], v[200:203], v[106:109]
	v_mfma_f32_16x16x32_bf16 v[94:97], v[70:73], v[212:215], v[94:97]
	v_mfma_f32_16x16x32_bf16 v[90:93], v[78:81], v[212:215], v[90:93]
	s_setprio 0
	s_setprio 1
	v_mfma_f32_16x16x32_bf16 v[134:137], v[164:167], v[180:183], v[134:137]
	v_mfma_f32_16x16x32_bf16 v[130:133], v[172:175], v[180:183], v[130:133]
	v_mfma_f32_16x16x32_bf16 v[118:121], v[164:167], v[188:191], v[118:121]
	v_mfma_f32_16x16x32_bf16 v[114:117], v[172:175], v[188:191], v[114:117]
	v_mfma_f32_16x16x32_bf16 v[102:105], v[164:167], v[196:199], v[102:105]
	v_mfma_f32_16x16x32_bf16 v[98:101], v[172:175], v[196:199], v[98:101]
	v_mfma_f32_16x16x32_bf16 v[86:89], v[164:167], v[204:207], v[86:89]
	v_mfma_f32_16x16x32_bf16 v[82:85], v[172:175], v[204:207], v[82:85]
	v_mfma_f32_16x16x32_bf16 v[134:137], v[168:171], v[184:187], v[134:137]
	v_mfma_f32_16x16x32_bf16 v[130:133], v[176:179], v[184:187], v[130:133]
	v_mfma_f32_16x16x32_bf16 v[118:121], v[168:171], v[192:195], v[118:121]
	v_mfma_f32_16x16x32_bf16 v[114:117], v[176:179], v[192:195], v[114:117]
	v_mfma_f32_16x16x32_bf16 v[102:105], v[168:171], v[200:203], v[102:105]
	v_mfma_f32_16x16x32_bf16 v[98:101], v[176:179], v[200:203], v[98:101]
	v_mfma_f32_16x16x32_bf16 v[86:89], v[168:171], v[212:215], v[86:89]
	v_mfma_f32_16x16x32_bf16 v[82:85], v[176:179], v[212:215], v[82:85]
	s_setprio 0
	s_barrier
	s_add_u32 s46, s22, 0x8000
	s_addc_u32 s47, s23, 0
	s_add_i32 s75, s75, s53
	s_mov_b32 m0, s75
	ds_read_b128 v[180:183], v161 offset:49152
	ds_read_b128 v[184:187], v161 offset:50176
	ds_read_b128 v[188:191], v161 offset:51200
	ds_read_b128 v[192:195], v161 offset:52224
	ds_read_b128 v[196:199], v161 offset:53248
	ds_read_b128 v[200:203], v161 offset:54272
	ds_read_b128 v[204:207], v161 offset:55296
	ds_read_b128 v[212:215], v161 offset:56320
	global_load_lds_dwordx4 v146, s[46:47]
	s_add_i32 m0, s75, 0x2000
	s_add_u32 s22, s22, 0xc000
	s_addc_u32 s23, s23, 0
	global_load_lds_dwordx4 v148, s[46:47]
	s_add_i32 s46, s76, s53
	s_mov_b32 m0, s46
	s_nop 0
	global_load_lds_dwordx4 v146, s[22:23]
	s_add_i32 m0, s46, 0x2000
	s_nop 0
	global_load_lds_dwordx4 v148, s[22:23]
	s_mov_b32 m0, s63
	s_nop 0
	global_load_lds_dwordx4 v152, s[16:17]
	s_mov_b32 m0, s64
	s_nop 0
	global_load_lds_dwordx4 v150, s[16:17]
	s_waitcnt vmcnt(8) lgkmcnt(0)
	s_barrier
	s_setprio 1
	v_mfma_f32_16x16x32_bf16 v[62:65], v[66:69], v[180:183], v[62:65]
	v_mfma_f32_16x16x32_bf16 v[58:61], v[74:77], v[180:183], v[58:61]
	v_mfma_f32_16x16x32_bf16 v[46:49], v[66:69], v[188:191], v[46:49]
	v_mfma_f32_16x16x32_bf16 v[42:45], v[74:77], v[188:191], v[42:45]
	v_mfma_f32_16x16x32_bf16 v[30:33], v[66:69], v[196:199], v[30:33]
	v_mfma_f32_16x16x32_bf16 v[26:29], v[74:77], v[196:199], v[26:29]
	v_mfma_f32_16x16x32_bf16 v[14:17], v[66:69], v[204:207], v[14:17]
	v_mfma_f32_16x16x32_bf16 v[10:13], v[74:77], v[204:207], v[10:13]
	v_mfma_f32_16x16x32_bf16 v[62:65], v[70:73], v[184:187], v[62:65]
	v_mfma_f32_16x16x32_bf16 v[58:61], v[78:81], v[184:187], v[58:61]
	v_mfma_f32_16x16x32_bf16 v[46:49], v[70:73], v[192:195], v[46:49]
	v_mfma_f32_16x16x32_bf16 v[42:45], v[78:81], v[192:195], v[42:45]
	v_mfma_f32_16x16x32_bf16 v[30:33], v[70:73], v[200:203], v[30:33]
	v_mfma_f32_16x16x32_bf16 v[26:29], v[78:81], v[200:203], v[26:29]
	v_mfma_f32_16x16x32_bf16 v[14:17], v[70:73], v[212:215], v[14:17]
	v_mfma_f32_16x16x32_bf16 v[10:13], v[78:81], v[212:215], v[10:13]
	s_setprio 0
	s_setprio 1
	v_mfma_f32_16x16x32_bf16 v[54:57], v[164:167], v[180:183], v[54:57]
	v_mfma_f32_16x16x32_bf16 v[50:53], v[172:175], v[180:183], v[50:53]
	v_mfma_f32_16x16x32_bf16 v[38:41], v[164:167], v[188:191], v[38:41]
	v_mfma_f32_16x16x32_bf16 v[34:37], v[172:175], v[188:191], v[34:37]
	v_mfma_f32_16x16x32_bf16 v[22:25], v[164:167], v[196:199], v[22:25]
	v_mfma_f32_16x16x32_bf16 v[18:21], v[172:175], v[196:199], v[18:21]
	v_mfma_f32_16x16x32_bf16 v[6:9], v[164:167], v[204:207], v[6:9]
	v_mfma_f32_16x16x32_bf16 v[2:5], v[172:175], v[204:207], v[2:5]
	v_mfma_f32_16x16x32_bf16 v[54:57], v[168:171], v[184:187], v[54:57]
	v_mfma_f32_16x16x32_bf16 v[50:53], v[176:179], v[184:187], v[50:53]
	v_mfma_f32_16x16x32_bf16 v[38:41], v[168:171], v[192:195], v[38:41]
	v_mfma_f32_16x16x32_bf16 v[34:37], v[176:179], v[192:195], v[34:37]
	v_mfma_f32_16x16x32_bf16 v[22:25], v[168:171], v[200:203], v[22:25]
	v_mfma_f32_16x16x32_bf16 v[18:21], v[176:179], v[200:203], v[18:21]
	v_mfma_f32_16x16x32_bf16 v[6:9], v[168:171], v[212:215], v[6:9]
	v_mfma_f32_16x16x32_bf16 v[2:5], v[176:179], v[212:215], v[2:5]
	s_setprio 0
	s_barrier
	s_add_u32 s14, s14, 2
	s_addc_u32 s15, s15, 0
	s_add_i32 s16, s14, -3
	s_add_u32 s73, s73, 0x10000
	s_addc_u32 s74, s74, 0
	s_cmp_gt_u32 s16, 29
	s_cbranch_scc0 .LBB0_1196
	s_and_b64 vcc, exec, s[26:27]
	s_cbranch_vccz .LBB0_1199
	s_barrier

.LBB0_1275:
	s_add_u32 s4, s2, 0x4000
	s_addc_u32 s5, s3, 0
	s_cmpk_eq_i32 s77, 0x52
	s_cselect_b32 s14, s54, s4
	s_cselect_b32 s15, s55, s5
	s_cselect_b32 s12, s56, s75
	s_cselect_b32 s13, s57, s76
	s_add_u32 s4, s14, 0x8000
	s_addc_u32 s5, s15, 0
	s_add_i32 s78, 0, 0x10000
	s_add_i32 s80, 0, 0x14000
	ds_read_b128 v[58:61], v229
	ds_read_b128 v[62:65], v229 offset:1024
	ds_read_b128 v[66:69], v229 offset:2048
	ds_read_b128 v[70:73], v229 offset:3072
	ds_read_b128 v[146:149], v229 offset:16384
	ds_read_b128 v[150:153], v229 offset:17408
	ds_read_b128 v[154:157], v229 offset:18432
	ds_read_b128 v[158:161], v229 offset:19456
	s_add_i32 m0, s59, 0xc000
	ds_read_b128 v[162:165], v225
	ds_read_b128 v[166:169], v225 offset:1024
	ds_read_b128 v[170:173], v225 offset:2048
	ds_read_b128 v[174:177], v225 offset:3072
	ds_read_b128 v[178:181], v225 offset:4096
	ds_read_b128 v[182:185], v225 offset:5120
	ds_read_b128 v[192:195], v225 offset:6144
	ds_read_b128 v[196:199], v225 offset:7168
	global_load_lds_dwordx4 v186, s[2:3]
	s_add_i32 m0, s59, 0xe000
	s_nop 0
	global_load_lds_dwordx4 v188, s[2:3]
	s_waitcnt vmcnt(8) lgkmcnt(0)
	s_barrier
	s_setprio 1
	v_mfma_f32_16x16x32_bf16 v[142:145], v[58:61], v[162:165], v[142:145]
	v_mfma_f32_16x16x32_bf16 v[138:141], v[66:69], v[162:165], v[138:141]
	v_mfma_f32_16x16x32_bf16 v[126:129], v[58:61], v[170:173], v[126:129]
	v_mfma_f32_16x16x32_bf16 v[122:125], v[66:69], v[170:173], v[122:125]
	v_mfma_f32_16x16x32_bf16 v[110:113], v[58:61], v[178:181], v[110:113]
	v_mfma_f32_16x16x32_bf16 v[106:109], v[66:69], v[178:181], v[106:109]
	v_mfma_f32_16x16x32_bf16 v[94:97], v[58:61], v[192:195], v[94:97]
	v_mfma_f32_16x16x32_bf16 v[90:93], v[66:69], v[192:195], v[90:93]
	v_mfma_f32_16x16x32_bf16 v[142:145], v[62:65], v[166:169], v[142:145]
	v_mfma_f32_16x16x32_bf16 v[138:141], v[70:73], v[166:169], v[138:141]
	v_mfma_f32_16x16x32_bf16 v[126:129], v[62:65], v[174:177], v[126:129]
	v_mfma_f32_16x16x32_bf16 v[122:125], v[70:73], v[174:177], v[122:125]
	v_mfma_f32_16x16x32_bf16 v[110:113], v[62:65], v[182:185], v[110:113]
	v_mfma_f32_16x16x32_bf16 v[106:109], v[70:73], v[182:185], v[106:109]
	v_mfma_f32_16x16x32_bf16 v[94:97], v[62:65], v[196:199], v[94:97]
	v_mfma_f32_16x16x32_bf16 v[90:93], v[70:73], v[196:199], v[90:93]
	s_setprio 0
	s_setprio 1
	v_mfma_f32_16x16x32_bf16 v[134:137], v[146:149], v[162:165], v[134:137]
	v_mfma_f32_16x16x32_bf16 v[130:133], v[154:157], v[162:165], v[130:133]
	v_mfma_f32_16x16x32_bf16 v[118:121], v[146:149], v[170:173], v[118:121]
	v_mfma_f32_16x16x32_bf16 v[114:117], v[154:157], v[170:173], v[114:117]
	v_mfma_f32_16x16x32_bf16 v[102:105], v[146:149], v[178:181], v[102:105]
	v_mfma_f32_16x16x32_bf16 v[98:101], v[154:157], v[178:181], v[98:101]
	v_mfma_f32_16x16x32_bf16 v[86:89], v[146:149], v[192:195], v[86:89]
	v_mfma_f32_16x16x32_bf16 v[82:85], v[154:157], v[192:195], v[82:85]
	v_mfma_f32_16x16x32_bf16 v[134:137], v[150:153], v[166:169], v[134:137]
	v_mfma_f32_16x16x32_bf16 v[130:133], v[158:161], v[166:169], v[130:133]
	v_mfma_f32_16x16x32_bf16 v[118:121], v[150:153], v[174:177], v[118:121]
	v_mfma_f32_16x16x32_bf16 v[114:117], v[158:161], v[174:177], v[114:117]
	v_mfma_f32_16x16x32_bf16 v[102:105], v[150:153], v[182:185], v[102:105]
	v_mfma_f32_16x16x32_bf16 v[98:101], v[158:161], v[182:185], v[98:101]
	v_mfma_f32_16x16x32_bf16 v[86:89], v[150:153], v[196:199], v[86:89]
	v_mfma_f32_16x16x32_bf16 v[82:85], v[158:161], v[196:199], v[82:85]
	s_setprio 0
	s_barrier
	s_add_i32 s78, s78, s58
	s_mov_b32 m0, s78
	ds_read_b128 v[162:165], v225 offset:16384
	ds_read_b128 v[166:169], v225 offset:17408
	ds_read_b128 v[170:173], v225 offset:18432
	ds_read_b128 v[174:177], v225 offset:19456
	ds_read_b128 v[178:181], v225 offset:20480
	ds_read_b128 v[182:185], v225 offset:21504
	ds_read_b128 v[192:195], v225 offset:22528
	ds_read_b128 v[196:199], v225 offset:23552
	global_load_lds_dwordx4 v186, s[12:13]
	s_add_i32 m0, s78, 0x2000
	s_add_u32 s78, s12, 0x4000
	s_addc_u32 s79, s13, 0
	s_add_i32 s80, s80, s58
	global_load_lds_dwordx4 v188, s[12:13]
	s_mov_b32 m0, s80
	s_nop 0
	global_load_lds_dwordx4 v186, s[78:79]
	s_add_i32 m0, s80, 0x2000
	s_nop 0
	global_load_lds_dwordx4 v188, s[78:79]
	s_mov_b32 m0, s59
	s_nop 0
	global_load_lds_dwordx4 v186, s[14:15]
	s_mov_b32 m0, s60
	s_nop 0
	global_load_lds_dwordx4 v188, s[14:15]
	s_waitcnt vmcnt(8) lgkmcnt(0)
	s_barrier
	s_setprio 1
	v_mfma_f32_16x16x32_bf16 v[78:81], v[58:61], v[162:165], v[78:81]
	v_mfma_f32_16x16x32_bf16 v[74:77], v[66:69], v[162:165], v[74:77]
	v_mfma_f32_16x16x32_bf16 v[46:49], v[58:61], v[170:173], v[46:49]
	v_mfma_f32_16x16x32_bf16 v[42:45], v[66:69], v[170:173], v[42:45]
	v_mfma_f32_16x16x32_bf16 v[30:33], v[58:61], v[178:181], v[30:33]
	v_mfma_f32_16x16x32_bf16 v[26:29], v[66:69], v[178:181], v[26:29]
	v_mfma_f32_16x16x32_bf16 v[14:17], v[58:61], v[192:195], v[14:17]
	v_mfma_f32_16x16x32_bf16 v[10:13], v[66:69], v[192:195], v[10:13]
	v_mfma_f32_16x16x32_bf16 v[78:81], v[62:65], v[166:169], v[78:81]
	v_mfma_f32_16x16x32_bf16 v[74:77], v[70:73], v[166:169], v[74:77]
	v_mfma_f32_16x16x32_bf16 v[46:49], v[62:65], v[174:177], v[46:49]
	v_mfma_f32_16x16x32_bf16 v[42:45], v[70:73], v[174:177], v[42:45]
	v_mfma_f32_16x16x32_bf16 v[30:33], v[62:65], v[182:185], v[30:33]
	v_mfma_f32_16x16x32_bf16 v[26:29], v[70:73], v[182:185], v[26:29]
	v_mfma_f32_16x16x32_bf16 v[14:17], v[62:65], v[196:199], v[14:17]
	v_mfma_f32_16x16x32_bf16 v[10:13], v[70:73], v[196:199], v[10:13]
	s_setprio 0
	s_setprio 1
	v_mfma_f32_16x16x32_bf16 v[54:57], v[146:149], v[162:165], v[54:57]
	v_mfma_f32_16x16x32_bf16 v[50:53], v[154:157], v[162:165], v[50:53]
	v_mfma_f32_16x16x32_bf16 v[38:41], v[146:149], v[170:173], v[38:41]
	v_mfma_f32_16x16x32_bf16 v[34:37], v[154:157], v[170:173], v[34:37]
	v_mfma_f32_16x16x32_bf16 v[22:25], v[146:149], v[178:181], v[22:25]
	v_mfma_f32_16x16x32_bf16 v[18:21], v[154:157], v[178:181], v[18:21]
	v_mfma_f32_16x16x32_bf16 v[6:9], v[146:149], v[192:195], v[6:9]
	v_mfma_f32_16x16x32_bf16 v[2:5], v[154:157], v[192:195], v[2:5]
	v_mfma_f32_16x16x32_bf16 v[54:57], v[150:153], v[166:169], v[54:57]
	v_mfma_f32_16x16x32_bf16 v[50:53], v[158:161], v[166:169], v[50:53]
	v_mfma_f32_16x16x32_bf16 v[38:41], v[150:153], v[174:177], v[38:41]
	v_mfma_f32_16x16x32_bf16 v[34:37], v[158:161], v[174:177], v[34:37]
	v_mfma_f32_16x16x32_bf16 v[22:25], v[150:153], v[182:185], v[22:25]
	v_mfma_f32_16x16x32_bf16 v[18:21], v[158:161], v[182:185], v[18:21]
	v_mfma_f32_16x16x32_bf16 v[6:9], v[150:153], v[196:199], v[6:9]
	v_mfma_f32_16x16x32_bf16 v[2:5], v[158:161], v[196:199], v[2:5]
	s_setprio 0
	s_barrier
	s_add_i32 s78, 0, 0x18000
	s_add_i32 s79, 0, 0x1c000
	ds_read_b128 v[58:61], v229 offset:32768
	ds_read_b128 v[62:65], v229 offset:33792
	ds_read_b128 v[66:69], v229 offset:34816
	ds_read_b128 v[70:73], v229 offset:35840
	ds_read_b128 v[146:149], v229 offset:49152
	ds_read_b128 v[150:153], v229 offset:50176
	ds_read_b128 v[154:157], v229 offset:51200
	ds_read_b128 v[158:161], v229 offset:52224
	s_add_u32 s14, s14, 0x4000
	s_addc_u32 s15, s15, 0
	s_mov_b32 m0, s61
	ds_read_b128 v[162:165], v225 offset:32768
	ds_read_b128 v[166:169], v225 offset:33792
	ds_read_b128 v[170:173], v225 offset:34816
	ds_read_b128 v[174:177], v225 offset:35840
	ds_read_b128 v[178:181], v225 offset:36864
	ds_read_b128 v[182:185], v225 offset:37888
	ds_read_b128 v[192:195], v225 offset:38912
	ds_read_b128 v[196:199], v225 offset:39936
	global_load_lds_dwordx4 v186, s[14:15]
	s_mov_b32 m0, s62
	s_nop 0
	global_load_lds_dwordx4 v188, s[14:15]
	s_waitcnt vmcnt(8) lgkmcnt(0)
	s_barrier
	s_setprio 1
	v_mfma_f32_16x16x32_bf16 v[142:145], v[58:61], v[162:165], v[142:145]
	v_mfma_f32_16x16x32_bf16 v[138:141], v[66:69], v[162:165], v[138:141]
	v_mfma_f32_16x16x32_bf16 v[126:129], v[58:61], v[170:173], v[126:129]
	v_mfma_f32_16x16x32_bf16 v[122:125], v[66:69], v[170:173], v[122:125]
	v_mfma_f32_16x16x32_bf16 v[110:113], v[58:61], v[178:181], v[110:113]
	v_mfma_f32_16x16x32_bf16 v[106:109], v[66:69], v[178:181], v[106:109]
	v_mfma_f32_16x16x32_bf16 v[94:97], v[58:61], v[192:195], v[94:97]
	v_mfma_f32_16x16x32_bf16 v[90:93], v[66:69], v[192:195], v[90:93]
	v_mfma_f32_16x16x32_bf16 v[142:145], v[62:65], v[166:169], v[142:145]
	v_mfma_f32_16x16x32_bf16 v[138:141], v[70:73], v[166:169], v[138:141]
	v_mfma_f32_16x16x32_bf16 v[126:129], v[62:65], v[174:177], v[126:129]
	v_mfma_f32_16x16x32_bf16 v[122:125], v[70:73], v[174:177], v[122:125]
	v_mfma_f32_16x16x32_bf16 v[110:113], v[62:65], v[182:185], v[110:113]
	v_mfma_f32_16x16x32_bf16 v[106:109], v[70:73], v[182:185], v[106:109]
	v_mfma_f32_16x16x32_bf16 v[94:97], v[62:65], v[196:199], v[94:97]
	v_mfma_f32_16x16x32_bf16 v[90:93], v[70:73], v[196:199], v[90:93]
	s_setprio 0
	s_setprio 1
	v_mfma_f32_16x16x32_bf16 v[134:137], v[146:149], v[162:165], v[134:137]
	v_mfma_f32_16x16x32_bf16 v[130:133], v[154:157], v[162:165], v[130:133]
	v_mfma_f32_16x16x32_bf16 v[118:121], v[146:149], v[170:173], v[118:121]
	v_mfma_f32_16x16x32_bf16 v[114:117], v[154:157], v[170:173], v[114:117]
	v_mfma_f32_16x16x32_bf16 v[102:105], v[146:149], v[178:181], v[102:105]
	v_mfma_f32_16x16x32_bf16 v[98:101], v[154:157], v[178:181], v[98:101]
	v_mfma_f32_16x16x32_bf16 v[86:89], v[146:149], v[192:195], v[86:89]
	v_mfma_f32_16x16x32_bf16 v[82:85], v[154:157], v[192:195], v[82:85]
	v_mfma_f32_16x16x32_bf16 v[134:137], v[150:153], v[166:169], v[134:137]
	v_mfma_f32_16x16x32_bf16 v[130:133], v[158:161], v[166:169], v[130:133]
	v_mfma_f32_16x16x32_bf16 v[118:121], v[150:153], v[174:177], v[118:121]
	v_mfma_f32_16x16x32_bf16 v[114:117], v[158:161], v[174:177], v[114:117]
	v_mfma_f32_16x16x32_bf16 v[102:105], v[150:153], v[182:185], v[102:105]
	v_mfma_f32_16x16x32_bf16 v[98:101], v[158:161], v[182:185], v[98:101]
	v_mfma_f32_16x16x32_bf16 v[86:89], v[150:153], v[196:199], v[86:89]
	v_mfma_f32_16x16x32_bf16 v[82:85], v[158:161], v[196:199], v[82:85]
	s_setprio 0
	s_barrier
	s_add_u32 s14, s12, 0x8000
	s_addc_u32 s15, s13, 0
	s_add_i32 s78, s78, s58
	s_mov_b32 m0, s78
	ds_read_b128 v[162:165], v225 offset:49152
	ds_read_b128 v[166:169], v225 offset:50176
	ds_read_b128 v[170:173], v225 offset:51200
	ds_read_b128 v[174:177], v225 offset:52224
	ds_read_b128 v[178:181], v225 offset:53248
	ds_read_b128 v[182:185], v225 offset:54272
	ds_read_b128 v[192:195], v225 offset:55296
	ds_read_b128 v[196:199], v225 offset:56320
	global_load_lds_dwordx4 v186, s[14:15]
	s_add_i32 m0, s78, 0x2000
	s_add_u32 s12, s12, 0xc000
	s_addc_u32 s13, s13, 0
	global_load_lds_dwordx4 v188, s[14:15]
	s_add_i32 s14, s79, s58
	s_mov_b32 m0, s14
	s_nop 0
	global_load_lds_dwordx4 v186, s[12:13]
	s_add_i32 m0, s14, 0x2000
	s_nop 0
	global_load_lds_dwordx4 v188, s[12:13]
	s_mov_b32 m0, s65
	s_nop 0
	global_load_lds_dwordx4 v186, s[4:5]
	s_mov_b32 m0, s66
	s_nop 0
	global_load_lds_dwordx4 v188, s[4:5]
	s_waitcnt vmcnt(8) lgkmcnt(0)
	s_barrier
	s_setprio 1
	v_mfma_f32_16x16x32_bf16 v[78:81], v[58:61], v[162:165], v[78:81]
	v_mfma_f32_16x16x32_bf16 v[74:77], v[66:69], v[162:165], v[74:77]
	v_mfma_f32_16x16x32_bf16 v[46:49], v[58:61], v[170:173], v[46:49]
	v_mfma_f32_16x16x32_bf16 v[42:45], v[66:69], v[170:173], v[42:45]
	v_mfma_f32_16x16x32_bf16 v[30:33], v[58:61], v[178:181], v[30:33]
	v_mfma_f32_16x16x32_bf16 v[26:29], v[66:69], v[178:181], v[26:29]
	v_mfma_f32_16x16x32_bf16 v[14:17], v[58:61], v[192:195], v[14:17]
	v_mfma_f32_16x16x32_bf16 v[10:13], v[66:69], v[192:195], v[10:13]
	v_mfma_f32_16x16x32_bf16 v[78:81], v[62:65], v[166:169], v[78:81]
	v_mfma_f32_16x16x32_bf16 v[74:77], v[70:73], v[166:169], v[74:77]
	v_mfma_f32_16x16x32_bf16 v[46:49], v[62:65], v[174:177], v[46:49]
	v_mfma_f32_16x16x32_bf16 v[42:45], v[70:73], v[174:177], v[42:45]
	v_mfma_f32_16x16x32_bf16 v[30:33], v[62:65], v[182:185], v[30:33]
	v_mfma_f32_16x16x32_bf16 v[26:29], v[70:73], v[182:185], v[26:29]
	v_mfma_f32_16x16x32_bf16 v[14:17], v[62:65], v[196:199], v[14:17]
	v_mfma_f32_16x16x32_bf16 v[10:13], v[70:73], v[196:199], v[10:13]
	s_setprio 0
	s_setprio 1
	v_mfma_f32_16x16x32_bf16 v[54:57], v[146:149], v[162:165], v[54:57]
	v_mfma_f32_16x16x32_bf16 v[50:53], v[154:157], v[162:165], v[50:53]
	v_mfma_f32_16x16x32_bf16 v[38:41], v[146:149], v[170:173], v[38:41]
	v_mfma_f32_16x16x32_bf16 v[34:37], v[154:157], v[170:173], v[34:37]
	v_mfma_f32_16x16x32_bf16 v[22:25], v[146:149], v[178:181], v[22:25]
	v_mfma_f32_16x16x32_bf16 v[18:21], v[154:157], v[178:181], v[18:21]
	v_mfma_f32_16x16x32_bf16 v[6:9], v[146:149], v[192:195], v[6:9]
	v_mfma_f32_16x16x32_bf16 v[2:5], v[154:157], v[192:195], v[2:5]
	v_mfma_f32_16x16x32_bf16 v[54:57], v[150:153], v[166:169], v[54:57]
	v_mfma_f32_16x16x32_bf16 v[50:53], v[158:161], v[166:169], v[50:53]
	v_mfma_f32_16x16x32_bf16 v[38:41], v[150:153], v[174:177], v[38:41]
	v_mfma_f32_16x16x32_bf16 v[34:37], v[158:161], v[174:177], v[34:37]
	v_mfma_f32_16x16x32_bf16 v[22:25], v[150:153], v[182:185], v[22:25]
	v_mfma_f32_16x16x32_bf16 v[18:21], v[158:161], v[182:185], v[18:21]
	v_mfma_f32_16x16x32_bf16 v[6:9], v[150:153], v[196:199], v[6:9]
	v_mfma_f32_16x16x32_bf16 v[2:5], v[158:161], v[196:199], v[2:5]
	s_setprio 0
	s_barrier
	s_add_i32 s77, s77, 2
	s_add_u32 s2, s2, 0x10000
	s_addc_u32 s3, s3, 0
	s_add_u32 s75, s75, 0x10000
	s_addc_u32 s76, s76, 0
	s_cmpk_gt_u32 s77, 0x53
	s_cbranch_scc0 .LBB0_1275
	s_and_b64 vcc, exec, s[48:49]
	s_cbranch_vccz .LBB0_1278
	s_barrier
